# adds: norm loops wait for the next-row prefetch only at the register rotation (counted vmcnt, global stores)
# baseline (speedup 1.0000x reference)
; #define GAS __attribute__((address_space(1)))
; #define ARG_IN(i) ((const float*)karg64(8 * (i)))
; #define ARG_WS() ((unsigned char*)karg64(8 * 19))
; #define REP(k) for (int rep_ = 0; rep_ < (DUP_PHASE == (k) ? 2 : 1); ++rep_, (DUP_PHASE == (k) ? xcd_barrier(bar) : (void)0))
; #define IDX() int tid = threadIdx.x, bid = blockIdx.x, G = gridDim.x; asm volatile("" : "+v"(tid)); asm volatile("" : "+s"(bid), "+s"(G)); \
;     const int lane = tid & 63, wave = __builtin_amdgcn_readfirstlane(tid >> 6), gw = bid * NWAVES + wave, NGW = G * NWAVES; (void)lane; (void)gw; (void)NGW; (void)wave
; __device__ __forceinline__ void norm_mod_rows_b(const bf16* src, const float* gain, const float* sh, const float* sc, bf16* dst, int gw, int NGW, int lane) {
;     v4u cur[4], nxt[4]; f32x4 A[8], B[8]; int cb = -1;
;     if (gw < M) { const GAS v4u* xr = (const GAS v4u*)(src + (size_t)gw * DM) + lane;
; #pragma unroll
;         for (int j = 0; j < 4; ++j) cur[j] = xr[64 * j]; }
; #pragma unroll 1
;     for (int m = gw; m < M; m += NGW) { const int b = m >> 12; const int mn = m + NGW < M ? m + NGW : m;
;         { const GAS v4u* xr = (const GAS v4u*)(src + (size_t)mn * DM) + lane;
; #pragma unroll
;             for (int j = 0; j < 4; ++j) nxt[j] = xr[64 * j]; }
;         if (b != cb) { cb = b;
; #pragma unroll
;             for (int j = 0; j < 4; ++j)
; #pragma unroll
;                 for (int h = 0; h < 2; ++h) { const int col = 8 * (64 * j + lane) + 4 * h;
;                     const f32x4 g4 = *(const GAS f32x4*)(gain + col), s4 = *(const GAS f32x4*)(sc + (size_t)b * NADA + col); A[2 * j + h] = g4 * (1.f + s4); B[2 * j + h] = *(const GAS f32x4*)(sh + (size_t)b * NADA + col); } }
; template <int PHM, int ATTM> __global__ void __launch_bounds__(NWAVES * 64, 2) fwd_kernel(Args args) {
;     ...
;         REP(1) if (IN(pb + 0) && EN(1)) { IDX(); unsigned char* ws = ARG_WS(); const float* mod = WSP(float, WS_MOD) + (size_t)layer * BATCH * NADA;
;             if (layer == 0) norm_mod_rows(ARG_IN(A_X), ARG_IN(A_GMIX) + (size_t)layer * DM, mod + 0, mod + DM, WSP(bf16, WS_U), gw, NGW, lane);
;             else norm_mod_rows_b(WSP(bf16, WS_H), ARG_IN(A_GMIX) + (size_t)layer * DM, mod + 0, mod + DM, WSP(bf16, WS_U), gw, NGW, lane); }
.LBB0_240:
	s_mul_i32 s2, s6, 9
	s_add_i32 s4, s2, 1
	s_cmp_le_i32 s68, s4
	v_writelane_b32 v255, s2, 20
	s_cselect_b64 s[2:3], -1, 0
	s_cmp_lt_i32 s4, s67
	s_mov_b32 s7, s19
	s_cselect_b64 s[4:5], -1, 0
	v_writelane_b32 v255, s6, 21
	s_and_b64 s[2:3], s[2:3], s[4:5]
	s_lshl_b64 s[4:5], s[6:7], 13
	v_writelane_b32 v255, s7, 22
	v_writelane_b32 v255, s4, 23
	s_andn2_b64 vcc, exec, s[2:3]
	s_nop 0
	v_writelane_b32 v255, s5, 24
	s_cbranch_vccnz .LBB0_254
	s_load_dword s5, s[72:73], 0x0
	v_mov_b32_e32 v1, v0
	s_mov_b32 s7, s66
	s_waitcnt lgkmcnt(0)
	s_load_dwordx2 s[22:23], s[0:1], 0x98
	v_readfirstlane_b32 s8, v1
	v_readlane_b32 s10, v255, 21
	s_ashr_i32 s8, s8, 6
	s_lshl_b32 s7, s7, 3
	s_mul_i32 s6, s10, 0x18000
	s_add_i32 s16, s7, s8
	s_lshl_b32 s14, s5, 3
	s_mul_hi_u32 s4, s10, 0x18000
	s_waitcnt lgkmcnt(0)
	s_add_u32 s5, s22, s6
	s_addc_u32 s6, s23, s4
	s_add_u32 s4, s5, 0x100000
	s_addc_u32 s5, s6, 0
	s_cmp_lg_u32 s10, 0
	s_waitcnt vmcnt(0)
	v_and_b32_e32 v100, 63, v1
	v_readlane_b32 s11, v255, 22
	s_cbranch_scc0 .LBB0_248
	s_load_dwordx2 s[20:21], s[0:1], 0x20
	s_cmpk_gt_i32 s16, 0x1fff
	s_cbranch_scc1 .LBB0_247
	s_add_u32 s6, s22, 0x4800000
	s_addc_u32 s7, s23, 0
	s_add_u32 s8, s4, 0x2000
	s_addc_u32 s9, s5, 0
	v_readlane_b32 s10, v255, 23
	v_readlane_b32 s11, v255, 24
	s_waitcnt lgkmcnt(0)
	s_add_u32 s10, s20, s10
	s_addc_u32 s11, s21, s11
	s_ashr_i32 s17, s16, 31
	s_lshl_b64 s[12:13], s[16:17], 12
	s_add_u32 s20, s6, s12
	s_addc_u32 s21, s7, s13
	v_lshlrev_b32_e32 v2, 4, v100
	global_load_dwordx4 v[32:35], v2, s[20:21]
	global_load_dwordx4 v[28:31], v2, s[20:21] offset:1024
	global_load_dwordx4 v[24:27], v2, s[20:21] offset:2048
	global_load_dwordx4 v[20:23], v2, s[20:21] offset:3072
	v_lshlrev_b32_e32 v4, 3, v100
	v_lshlrev_b32_e32 v6, 5, v100
	v_mov_b32_e32 v7, v3
	v_lshl_add_u64 v[102:103], s[10:11], 0, v[6:7]
	v_or_b32_e32 v6, 0x400, v4
	v_lshlrev_b32_e32 v8, 2, v6
	v_mov_b32_e32 v9, v3
	v_lshl_add_u64 v[104:105], s[10:11], 0, v[8:9]
	v_or_b32_e32 v8, 0x600, v4
	v_lshlrev_b32_e32 v10, 2, v8
	v_mov_b32_e32 v11, v3
	v_lshl_add_u64 v[106:107], s[10:11], 0, v[10:11]
	s_add_u32 s10, s22, s12
	s_addc_u32 s11, s23, s13
	v_lshl_add_u64 v[10:11], s[10:11], 0, v[2:3]
	s_mov_b64 s[10:11], 0x800000
	s_ashr_i32 s15, s14, 31
	v_lshl_add_u64 v[108:109], v[10:11], 0, s[10:11]
	s_lshl_b64 s[20:21], s[14:15], 12
	s_mov_b32 s12, -1
	v_lshlrev_b32_e32 v1, 4, v100
	v_lshlrev_b32_e32 v2, 2, v4
	v_lshlrev_b32_e32 v101, 2, v6
	v_lshlrev_b32_e32 v110, 2, v8
	s_mov_b32 s10, s16
	s_waitcnt vmcnt(0)
	s_branch .LBB0_245
; __device__ __forceinline__ unsigned pk2(float lo, float hi) { pk2_f2_t v = {lo, hi}; pk2_b2_t b = __builtin_convertvector(v, pk2_b2_t); return __builtin_bit_cast(unsigned, b); }
; __device__ __forceinline__ float wave_sum(float v) { v += lx<1>(v); v += lx<2>(v); v += lx<4>(v); v += lx<8>(v); v += lx<16>(v); return half_sum(v); }
; __device__ __forceinline__ void norm_mod_rows_b(const bf16* src, const float* gain, const float* sh, const float* sc, bf16* dst, int gw, int NGW, int lane) {
;     ...
;         __builtin_amdgcn_sched_barrier(0);
;         f32x4 x[8];
; #pragma unroll
;         for (int j = 0; j < 4; ++j) { x[2 * j] = (f32x4){lo16(cur[j].x), hi16(cur[j].x), lo16(cur[j].y), hi16(cur[j].y)}; x[2 * j + 1] = (f32x4){lo16(cur[j].z), hi16(cur[j].z), lo16(cur[j].w), hi16(cur[j].w)}; }
;         float ss = 0.f;
; #pragma unroll
;         for (int j = 0; j < 8; ++j) ss += (x[j].x * x[j].x + x[j].y * x[j].y) + (x[j].z * x[j].z + x[j].w * x[j].w);
;         const float rstd = rsqrtf(wave_sum(ss) * (1.f / DM) + 1e-6f);
;         v4u* o16 = (v4u*)(dst + (size_t)m * DM) + lane;
; #pragma unroll
;         for (int j = 0; j < 4; ++j) { const f32x4 y0 = x[2 * j] * rstd * A[2 * j] + B[2 * j], y1 = x[2 * j + 1] * rstd * A[2 * j + 1] + B[2 * j + 1];
;             v4u w; w.x = pk2(y0.x, y0.y); w.y = pk2(y0.z, y0.w); w.z = pk2(y1.x, y1.y); w.w = pk2(y1.z, y1.w); o16[64 * j] = w; }
; #pragma unroll
;         for (int j = 0; j < 4; ++j) cur[j] = nxt[j];
.LBB0_244:
	v_lshlrev_b32_e32 v112, 16, v32
	v_and_b32_e32 v113, 0xffff0000, v32
	v_lshlrev_b32_e32 v32, 16, v33
	v_and_b32_e32 v33, 0xffff0000, v33
	v_lshlrev_b32_e32 v124, 16, v20
	v_and_b32_e32 v125, 0xffff0000, v20
	v_lshlrev_b32_e32 v126, 16, v21
	v_and_b32_e32 v127, 0xffff0000, v21
	v_mul_f32_e32 v20, v113, v113
	v_mul_f32_e32 v21, v33, v33
	v_lshlrev_b32_e32 v114, 16, v34
	v_and_b32_e32 v115, 0xffff0000, v34
	v_lshlrev_b32_e32 v34, 16, v35
	v_and_b32_e32 v35, 0xffff0000, v35
	v_fmac_f32_e32 v20, v112, v112
	v_fmac_f32_e32 v21, v32, v32
	v_lshlrev_b32_e32 v128, 16, v22
	v_and_b32_e32 v129, 0xffff0000, v22
	v_add_f32_e32 v20, v20, v21
	v_mul_f32_e32 v21, v115, v115
	v_mul_f32_e32 v22, v35, v35
	v_fmac_f32_e32 v21, v114, v114
	v_fmac_f32_e32 v22, v34, v34
	v_lshlrev_b32_e32 v116, 16, v28
	v_and_b32_e32 v117, 0xffff0000, v28
	v_lshlrev_b32_e32 v28, 16, v29
	v_and_b32_e32 v29, 0xffff0000, v29
	v_add_f32_e32 v21, v21, v22
	v_add_f32_e32 v20, v20, v21
	v_mul_f32_e32 v21, v117, v117
	v_mul_f32_e32 v22, v29, v29
	v_fmac_f32_e32 v21, v116, v116
	v_fmac_f32_e32 v22, v28, v28
	v_lshlrev_b32_e32 v118, 16, v30
	v_and_b32_e32 v119, 0xffff0000, v30
	v_lshlrev_b32_e32 v30, 16, v31
	v_and_b32_e32 v31, 0xffff0000, v31
	v_add_f32_e32 v21, v21, v22
	v_add_f32_e32 v20, v20, v21
	v_mul_f32_e32 v21, v119, v119
	v_mul_f32_e32 v22, v31, v31
	v_fmac_f32_e32 v21, v118, v118
	v_fmac_f32_e32 v22, v30, v30
	v_lshlrev_b32_e32 v120, 16, v24
	v_and_b32_e32 v121, 0xffff0000, v24
	v_lshlrev_b32_e32 v24, 16, v25
	v_and_b32_e32 v25, 0xffff0000, v25
	v_add_f32_e32 v21, v21, v22
	v_add_f32_e32 v20, v21, v20
	v_mul_f32_e32 v21, v121, v121
	v_mul_f32_e32 v22, v25, v25
	v_fmac_f32_e32 v21, v120, v120
	v_fmac_f32_e32 v22, v24, v24
	v_lshlrev_b32_e32 v122, 16, v26
	v_and_b32_e32 v123, 0xffff0000, v26
	v_lshlrev_b32_e32 v26, 16, v27
	v_and_b32_e32 v27, 0xffff0000, v27
	v_add_f32_e32 v21, v21, v22
	v_add_f32_e32 v20, v21, v20
	v_mul_f32_e32 v21, v123, v123
	v_mul_f32_e32 v22, v27, v27
	v_fmac_f32_e32 v21, v122, v122
	v_fmac_f32_e32 v22, v26, v26
	v_add_f32_e32 v21, v21, v22
	v_add_f32_e32 v20, v21, v20
	v_mul_f32_e32 v21, v125, v125
	v_mul_f32_e32 v22, v127, v127
	v_fmac_f32_e32 v21, v124, v124
	v_fmac_f32_e32 v22, v126, v126
	v_and_b32_e32 v131, 0xffff0000, v23
	v_add_f32_e32 v21, v21, v22
	v_lshlrev_b32_e32 v130, 16, v23
	v_add_f32_e32 v20, v21, v20
	v_mul_f32_e32 v21, v129, v129
	v_mul_f32_e32 v22, v131, v131
	v_fmac_f32_e32 v21, v128, v128
	v_fmac_f32_e32 v22, v130, v130
	v_add_f32_e32 v21, v21, v22
	v_add_f32_e32 v20, v21, v20
	ds_swizzle_b32 v21, v20 offset:swizzle(SWAP,1)
	s_mov_b32 s11, 0x800000
	s_waitcnt lgkmcnt(0)
	v_add_f32_e32 v20, v20, v21
	ds_swizzle_b32 v21, v20 offset:swizzle(SWAP,2)
	s_waitcnt lgkmcnt(0)
	v_add_f32_e32 v20, v20, v21
	ds_swizzle_b32 v21, v20 offset:swizzle(SWAP,4)
	s_waitcnt lgkmcnt(0)
	v_add_f32_e32 v20, v20, v21
	ds_swizzle_b32 v21, v20 offset:swizzle(SWAP,8)
	s_waitcnt lgkmcnt(0)
	v_add_f32_e32 v20, v20, v21
	ds_swizzle_b32 v21, v20 offset:swizzle(SWAP,16)
	s_waitcnt lgkmcnt(0)
	v_add_f32_e32 v20, v20, v21
	v_mov_b32_e32 v21, v20
	s_nop 1
	v_permlane32_swap_b32_e32 v20, v21
	v_add_f32_e32 v20, v20, v21
	v_fmamk_f32 v20, v20, 0x3a000000, v228
	v_mul_f32_e32 v21, 0x4b800000, v20
	v_cmp_gt_f32_e32 vcc, s11, v20
	s_nop 1
	v_cndmask_b32_e32 v20, v20, v21, vcc
	v_rsq_f32_e32 v20, v20
	s_nop 0
	v_mul_f32_e32 v21, 0x45800000, v20
	v_cndmask_b32_e32 v132, v20, v21, vcc
	v_pk_mul_f32 v[20:21], v[112:113], v[132:133] op_sel_hi:[1,0]
	v_pk_mul_f32 v[22:23], v[32:33], v[132:133] op_sel_hi:[1,0]
	v_pk_mul_f32 v[32:33], v[114:115], v[132:133] op_sel_hi:[1,0]
	v_pk_mul_f32 v[34:35], v[34:35], v[132:133] op_sel_hi:[1,0]
	v_pk_fma_f32 v[22:23], v[70:71], v[22:23], v[58:59]
	v_pk_fma_f32 v[20:21], v[68:69], v[20:21], v[56:57]
	v_pk_fma_f32 v[34:35], v[74:75], v[34:35], v[46:47]
	v_pk_fma_f32 v[32:33], v[72:73], v[32:33], v[44:45]
	v_cvt_pk_bf16_f32 v20, v20, v21
	v_cvt_pk_bf16_f32 v21, v22, v23
	v_cvt_pk_bf16_f32 v22, v32, v33
	v_cvt_pk_bf16_f32 v23, v34, v35
	global_store_dwordx4 v[108:109], v[20:23], off
	v_pk_mul_f32 v[30:31], v[30:31], v[132:133] op_sel_hi:[1,0]
	v_pk_mul_f32 v[26:27], v[26:27], v[132:133] op_sel_hi:[1,0]
	v_pk_mul_f32 v[20:21], v[116:117], v[132:133] op_sel_hi:[1,0]
	v_pk_mul_f32 v[22:23], v[28:29], v[132:133] op_sel_hi:[1,0]
	v_pk_mul_f32 v[28:29], v[118:119], v[132:133] op_sel_hi:[1,0]
	v_pk_fma_f32 v[22:23], v[78:79], v[22:23], v[54:55]
	v_pk_fma_f32 v[20:21], v[76:77], v[20:21], v[52:53]
	v_pk_fma_f32 v[30:31], v[82:83], v[30:31], v[42:43]
	v_pk_fma_f32 v[28:29], v[80:81], v[28:29], v[40:41]
	v_cvt_pk_bf16_f32 v20, v20, v21
	v_cvt_pk_bf16_f32 v21, v22, v23
	v_cvt_pk_bf16_f32 v22, v28, v29
	v_cvt_pk_bf16_f32 v23, v30, v31
	global_store_dwordx4 v[108:109], v[20:23], off offset:1024
	v_pk_fma_f32 v[26:27], v[90:91], v[26:27], v[38:39]
	s_waitcnt vmcnt(2)
	v_mov_b64_e32 v[34:35], v[6:7]
	v_pk_mul_f32 v[20:21], v[120:121], v[132:133] op_sel_hi:[1,0]
	v_pk_mul_f32 v[22:23], v[24:25], v[132:133] op_sel_hi:[1,0]
	v_pk_mul_f32 v[24:25], v[122:123], v[132:133] op_sel_hi:[1,0]
	v_pk_fma_f32 v[22:23], v[86:87], v[22:23], v[50:51]
	v_pk_fma_f32 v[20:21], v[84:85], v[20:21], v[48:49]
	v_pk_fma_f32 v[24:25], v[88:89], v[24:25], v[36:37]
	v_cvt_pk_bf16_f32 v20, v20, v21
	v_cvt_pk_bf16_f32 v21, v22, v23
	v_cvt_pk_bf16_f32 v22, v24, v25
	v_cvt_pk_bf16_f32 v23, v26, v27
	global_store_dwordx4 v[108:109], v[20:23], off offset:2048
	v_pk_mul_f32 v[24:25], v[128:129], v[132:133] op_sel_hi:[1,0]
	v_pk_mul_f32 v[26:27], v[130:131], v[132:133] op_sel_hi:[1,0]
	v_pk_mul_f32 v[20:21], v[124:125], v[132:133] op_sel_hi:[1,0]
	v_pk_mul_f32 v[22:23], v[126:127], v[132:133] op_sel_hi:[1,0]
	v_pk_fma_f32 v[20:21], v[92:93], v[20:21], v[64:65]
	v_pk_fma_f32 v[22:23], v[94:95], v[22:23], v[66:67]
	v_pk_fma_f32 v[26:27], v[98:99], v[26:27], v[62:63]
	v_pk_fma_f32 v[24:25], v[96:97], v[24:25], v[60:61]
	v_cvt_pk_bf16_f32 v20, v20, v21
	v_cvt_pk_bf16_f32 v21, v22, v23
	v_cvt_pk_bf16_f32 v22, v24, v25
	v_cvt_pk_bf16_f32 v23, v26, v27
	global_store_dwordx4 v[108:109], v[20:23], off offset:3072
	v_mov_b64_e32 v[30:31], v[10:11]
	v_mov_b64_e32 v[26:27], v[14:15]
	v_mov_b64_e32 v[22:23], v[18:19]
	v_lshl_add_u64 v[108:109], v[108:109], 0, s[20:21]
	s_andn2_b64 vcc, exec, s[24:25]
	v_mov_b64_e32 v[32:33], v[4:5]
	v_mov_b64_e32 v[28:29], v[8:9]
	v_mov_b64_e32 v[24:25], v[12:13]
	v_mov_b64_e32 v[20:21], v[16:17]
	s_cbranch_vccz .LBB0_247

; __device__ __forceinline__ unsigned pk2(float lo, float hi) { pk2_f2_t v = {lo, hi}; pk2_b2_t b = __builtin_convertvector(v, pk2_b2_t); return __builtin_bit_cast(unsigned, b); }
; __device__ __forceinline__ float wave_sum(float v) { v += lx<1>(v); v += lx<2>(v); v += lx<4>(v); v += lx<8>(v); v += lx<16>(v); return half_sum(v); }
; __device__ __forceinline__ void norm_mod_rows_b(const bf16* src, const float* gain, const float* sh, const float* sc, bf16* dst, int gw, int NGW, int lane) {
;     ...
;         __builtin_amdgcn_sched_barrier(0);
;         f32x4 x[8];
; #pragma unroll
;         for (int j = 0; j < 4; ++j) { x[2 * j] = (f32x4){lo16(cur[j].x), hi16(cur[j].x), lo16(cur[j].y), hi16(cur[j].y)}; x[2 * j + 1] = (f32x4){lo16(cur[j].z), hi16(cur[j].z), lo16(cur[j].w), hi16(cur[j].w)}; }
;         float ss = 0.f;
; #pragma unroll
;         for (int j = 0; j < 8; ++j) ss += (x[j].x * x[j].x + x[j].y * x[j].y) + (x[j].z * x[j].z + x[j].w * x[j].w);
;         const float rstd = rsqrtf(wave_sum(ss) * (1.f / DM) + 1e-6f);
;         v4u* o16 = (v4u*)(dst + (size_t)m * DM) + lane;
; #pragma unroll
;         for (int j = 0; j < 4; ++j) { const f32x4 y0 = x[2 * j] * rstd * A[2 * j] + B[2 * j], y1 = x[2 * j + 1] * rstd * A[2 * j + 1] + B[2 * j + 1];
;             v4u w; w.x = pk2(y0.x, y0.y); w.y = pk2(y0.z, y0.w); w.z = pk2(y1.x, y1.y); w.w = pk2(y1.z, y1.w); o16[64 * j] = w; }
; #pragma unroll
;         for (int j = 0; j < 4; ++j) cur[j] = nxt[j];
.LBB0_2106:
	v_lshlrev_b32_e32 v110, 16, v32
	v_and_b32_e32 v111, 0xffff0000, v32
	v_lshlrev_b32_e32 v32, 16, v33
	v_and_b32_e32 v33, 0xffff0000, v33
	v_lshlrev_b32_e32 v122, 16, v20
	v_and_b32_e32 v123, 0xffff0000, v20
	v_lshlrev_b32_e32 v124, 16, v21
	v_and_b32_e32 v125, 0xffff0000, v21
	v_mul_f32_e32 v20, v111, v111
	v_mul_f32_e32 v21, v33, v33
	v_lshlrev_b32_e32 v112, 16, v34
	v_and_b32_e32 v113, 0xffff0000, v34
	v_lshlrev_b32_e32 v34, 16, v35
	v_and_b32_e32 v35, 0xffff0000, v35
	v_fmac_f32_e32 v20, v110, v110
	v_fmac_f32_e32 v21, v32, v32
	v_lshlrev_b32_e32 v126, 16, v22
	v_and_b32_e32 v127, 0xffff0000, v22
	v_add_f32_e32 v20, v20, v21
	v_mul_f32_e32 v21, v113, v113
	v_mul_f32_e32 v22, v35, v35
	v_fmac_f32_e32 v21, v112, v112
	v_fmac_f32_e32 v22, v34, v34
	v_lshlrev_b32_e32 v114, 16, v28
	v_and_b32_e32 v115, 0xffff0000, v28
	v_lshlrev_b32_e32 v28, 16, v29
	v_and_b32_e32 v29, 0xffff0000, v29
	v_add_f32_e32 v21, v21, v22
	v_add_f32_e32 v20, v20, v21
	v_mul_f32_e32 v21, v115, v115
	v_mul_f32_e32 v22, v29, v29
	v_fmac_f32_e32 v21, v114, v114
	v_fmac_f32_e32 v22, v28, v28
	v_lshlrev_b32_e32 v116, 16, v30
	v_and_b32_e32 v117, 0xffff0000, v30
	v_lshlrev_b32_e32 v30, 16, v31
	v_and_b32_e32 v31, 0xffff0000, v31
	v_add_f32_e32 v21, v21, v22
	v_add_f32_e32 v20, v20, v21
	v_mul_f32_e32 v21, v117, v117
	v_mul_f32_e32 v22, v31, v31
	v_fmac_f32_e32 v21, v116, v116
	v_fmac_f32_e32 v22, v30, v30
	v_lshlrev_b32_e32 v118, 16, v24
	v_and_b32_e32 v119, 0xffff0000, v24
	v_lshlrev_b32_e32 v24, 16, v25
	v_and_b32_e32 v25, 0xffff0000, v25
	v_add_f32_e32 v21, v21, v22
	v_add_f32_e32 v20, v21, v20
	v_mul_f32_e32 v21, v119, v119
	v_mul_f32_e32 v22, v25, v25
	v_fmac_f32_e32 v21, v118, v118
	v_fmac_f32_e32 v22, v24, v24
	v_lshlrev_b32_e32 v120, 16, v26
	v_and_b32_e32 v121, 0xffff0000, v26
	v_lshlrev_b32_e32 v26, 16, v27
	v_and_b32_e32 v27, 0xffff0000, v27
	v_add_f32_e32 v21, v21, v22
	v_add_f32_e32 v20, v21, v20
	v_mul_f32_e32 v21, v121, v121
	v_mul_f32_e32 v22, v27, v27
	v_fmac_f32_e32 v21, v120, v120
	v_fmac_f32_e32 v22, v26, v26
	v_add_f32_e32 v21, v21, v22
	v_add_f32_e32 v20, v21, v20
	v_mul_f32_e32 v21, v123, v123
	v_mul_f32_e32 v22, v125, v125
	v_fmac_f32_e32 v21, v122, v122
	v_fmac_f32_e32 v22, v124, v124
	v_and_b32_e32 v129, 0xffff0000, v23
	v_add_f32_e32 v21, v21, v22
	v_lshlrev_b32_e32 v128, 16, v23
	v_add_f32_e32 v20, v21, v20
	v_mul_f32_e32 v21, v127, v127
	v_mul_f32_e32 v22, v129, v129
	v_fmac_f32_e32 v21, v126, v126
	v_fmac_f32_e32 v22, v128, v128
	v_add_f32_e32 v21, v21, v22
	v_add_f32_e32 v20, v21, v20
	ds_swizzle_b32 v21, v20 offset:swizzle(SWAP,1)
	s_mov_b32 s3, 0x800000
	s_waitcnt lgkmcnt(0)
	v_add_f32_e32 v20, v20, v21
	ds_swizzle_b32 v21, v20 offset:swizzle(SWAP,2)
	s_waitcnt lgkmcnt(0)
	v_add_f32_e32 v20, v20, v21
	ds_swizzle_b32 v21, v20 offset:swizzle(SWAP,4)
	s_waitcnt lgkmcnt(0)
	v_add_f32_e32 v20, v20, v21
	ds_swizzle_b32 v21, v20 offset:swizzle(SWAP,8)
	s_waitcnt lgkmcnt(0)
	v_add_f32_e32 v20, v20, v21
	ds_swizzle_b32 v21, v20 offset:swizzle(SWAP,16)
	s_waitcnt lgkmcnt(0)
	v_add_f32_e32 v20, v20, v21
	v_mov_b32_e32 v21, v20
	s_nop 1
	v_permlane32_swap_b32_e32 v20, v21
	v_add_f32_e32 v20, v20, v21
	v_fmamk_f32 v20, v20, 0x3a000000, v228
	v_mul_f32_e32 v21, 0x4b800000, v20
	v_cmp_gt_f32_e32 vcc, s3, v20
	s_nop 1
	v_cndmask_b32_e32 v20, v20, v21, vcc
	v_rsq_f32_e32 v20, v20
	s_nop 0
	v_mul_f32_e32 v21, 0x45800000, v20
	v_cndmask_b32_e32 v130, v20, v21, vcc
	v_pk_mul_f32 v[20:21], v[110:111], v[130:131] op_sel_hi:[1,0]
	v_pk_mul_f32 v[22:23], v[32:33], v[130:131] op_sel_hi:[1,0]
	v_pk_mul_f32 v[32:33], v[112:113], v[130:131] op_sel_hi:[1,0]
	v_pk_mul_f32 v[34:35], v[34:35], v[130:131] op_sel_hi:[1,0]
	v_pk_fma_f32 v[22:23], v[70:71], v[22:23], v[58:59]
	v_pk_fma_f32 v[20:21], v[68:69], v[20:21], v[56:57]
	v_pk_fma_f32 v[34:35], v[74:75], v[34:35], v[46:47]
	v_pk_fma_f32 v[32:33], v[72:73], v[32:33], v[44:45]
	v_cvt_pk_bf16_f32 v20, v20, v21
	v_cvt_pk_bf16_f32 v21, v22, v23
	v_cvt_pk_bf16_f32 v22, v32, v33
	v_cvt_pk_bf16_f32 v23, v34, v35
	global_store_dwordx4 v[106:107], v[20:23], off
	v_pk_mul_f32 v[30:31], v[30:31], v[130:131] op_sel_hi:[1,0]
	v_pk_mul_f32 v[26:27], v[26:27], v[130:131] op_sel_hi:[1,0]
	v_pk_mul_f32 v[20:21], v[114:115], v[130:131] op_sel_hi:[1,0]
	v_pk_mul_f32 v[22:23], v[28:29], v[130:131] op_sel_hi:[1,0]
	v_pk_mul_f32 v[28:29], v[116:117], v[130:131] op_sel_hi:[1,0]
	v_pk_fma_f32 v[22:23], v[78:79], v[22:23], v[54:55]
	v_pk_fma_f32 v[20:21], v[76:77], v[20:21], v[52:53]
	v_pk_fma_f32 v[30:31], v[82:83], v[30:31], v[42:43]
	v_pk_fma_f32 v[28:29], v[80:81], v[28:29], v[40:41]
	v_cvt_pk_bf16_f32 v20, v20, v21
	v_cvt_pk_bf16_f32 v21, v22, v23
	v_cvt_pk_bf16_f32 v22, v28, v29
	v_cvt_pk_bf16_f32 v23, v30, v31
	global_store_dwordx4 v[106:107], v[20:23], off offset:1024
	v_pk_fma_f32 v[26:27], v[90:91], v[26:27], v[38:39]
	s_waitcnt vmcnt(2)
	v_mov_b64_e32 v[34:35], v[6:7]
	v_pk_mul_f32 v[20:21], v[118:119], v[130:131] op_sel_hi:[1,0]
	v_pk_mul_f32 v[22:23], v[24:25], v[130:131] op_sel_hi:[1,0]
	v_pk_mul_f32 v[24:25], v[120:121], v[130:131] op_sel_hi:[1,0]
	v_pk_fma_f32 v[22:23], v[86:87], v[22:23], v[50:51]
	v_pk_fma_f32 v[20:21], v[84:85], v[20:21], v[48:49]
	v_pk_fma_f32 v[24:25], v[88:89], v[24:25], v[36:37]
	v_cvt_pk_bf16_f32 v20, v20, v21
	v_cvt_pk_bf16_f32 v21, v22, v23
	v_cvt_pk_bf16_f32 v22, v24, v25
	v_cvt_pk_bf16_f32 v23, v26, v27
	global_store_dwordx4 v[106:107], v[20:23], off offset:2048
	v_pk_mul_f32 v[24:25], v[126:127], v[130:131] op_sel_hi:[1,0]
	v_pk_mul_f32 v[26:27], v[128:129], v[130:131] op_sel_hi:[1,0]
	v_pk_mul_f32 v[20:21], v[122:123], v[130:131] op_sel_hi:[1,0]
	v_pk_mul_f32 v[22:23], v[124:125], v[130:131] op_sel_hi:[1,0]
	v_pk_fma_f32 v[20:21], v[92:93], v[20:21], v[64:65]
	v_pk_fma_f32 v[22:23], v[94:95], v[22:23], v[66:67]
	v_pk_fma_f32 v[26:27], v[98:99], v[26:27], v[62:63]
	v_pk_fma_f32 v[24:25], v[96:97], v[24:25], v[60:61]
	v_cvt_pk_bf16_f32 v20, v20, v21
	v_cvt_pk_bf16_f32 v21, v22, v23
	v_cvt_pk_bf16_f32 v22, v24, v25
	v_cvt_pk_bf16_f32 v23, v26, v27
	global_store_dwordx4 v[106:107], v[20:23], off offset:3072
	v_mov_b64_e32 v[30:31], v[10:11]
	v_mov_b64_e32 v[26:27], v[14:15]
	v_mov_b64_e32 v[22:23], v[18:19]
	v_lshl_add_u64 v[106:107], v[106:107], 0, s[16:17]
	s_andn2_b64 vcc, exec, s[20:21]
	v_mov_b64_e32 v[32:33], v[4:5]
	v_mov_b64_e32 v[28:29], v[8:9]
	v_mov_b64_e32 v[24:25], v[12:13]
	v_mov_b64_e32 v[20:21], v[16:17]
	s_cbranch_vccz .LBB0_2109
